# s5 state-scan units: all 8 u-fragments of a unit loaded up front; recurrence as 4 scalar FMAs per token
# speedup vs baseline: 1.0007x; 1.0007x over previous
; __device__ __forceinline__ void s5_setup(const Params& P, int g, int p, float& ar, float& ai, float (&Br)[16], float (&Bi)[16]) {
;     ...
;     const float lre = P.in[10][gp], lim = P.in[11][gp], dt = expf(P.in[12][gp]);
;     const float zr = lre * dt, zi = lim * dt; const float er = expf(zr); float sn, cs; sincosf(zi, &sn, &cs);
;     ar = er * cs; ai = er * sn;
;     const float nr = ar - 1.0f, ni = ai, den = 1.0f / (lre * lre + lim * lim);
;     const float cr = (nr * lre + ni * lim) * den, ci = (ni * lre - nr * lim) * den;
;     const f32x4* bre = (const f32x4*)(P.in[13] + (size_t)gp * 16); const f32x4* bim = (const f32x4*)(P.in[14] + (size_t)gp * 16);
; #pragma unroll
;     for (int c4 = 0; c4 < 4; ++c4) { const f32x4 x = bre[c4], y = bim[c4];
; #pragma unroll
;         for (int e = 0; e < 4; ++e) { Br[c4 * 4 + e] = cr * x[e] - ci * y[e]; Bi[c4 * 4 + e] = cr * y[e] + ci * x[e]; } }
.LBB0_365:
	s_or_b64 exec, exec, s[0:1]
	s_waitcnt vmcnt(0)
	v_mul_f32_e32 v6, v34, v6
	v_mul_f32_e32 v9, 0x3fb8aa3b, v6
	v_fma_f32 v10, v6, s33, -v9
	v_rndne_f32_e32 v11, v9
	v_fmac_f32_e32 v10, 0x32a5705f, v6
	v_sub_f32_e32 v9, v9, v11
	v_add_f32_e32 v9, v9, v10
	v_exp_f32_e32 v9, v9
	v_cvt_i32_f32_e32 v10, v11
	v_cmp_ngt_f32_e32 vcc, s55, v6
	v_xor_b32_e32 v5, v5, v4
	v_readlane_b32 s56, v245, 2
	v_ldexp_f32 v9, v9, v10
	v_cndmask_b32_e32 v9, 0, v9, vcc
	v_cmp_nlt_f32_e32 vcc, s50, v6
	v_lshlrev_b64 v[2:3], 6, v[2:3]
	v_readlane_b32 s66, v245, 12
	v_cndmask_b32_e32 v6, v227, v9, vcc
	v_mul_f32_e32 v9, v7, v7
	v_fmamk_f32 v10, v9, 0xb94c1982, v220
	v_fmaak_f32 v10, v9, v10, 0xbe2aaa9d
	v_mul_f32_e32 v10, v9, v10
	v_fmac_f32_e32 v7, v7, v10
	v_fmamk_f32 v10, v9, 0x37d75334, v221
	v_fmaak_f32 v10, v9, v10, 0x3d2aabf7
	v_fmaak_f32 v10, v9, v10, 0xbf000004
	v_fma_f32 v9, v9, v10, 1.0
	v_lshlrev_b32_e32 v10, 30, v8
	v_and_b32_e32 v8, 1, v8
	v_cmp_eq_u32_e32 vcc, 0, v8
	v_and_b32_e32 v10, 0x80000000, v10
	v_readlane_b32 s67, v245, 13
	v_cndmask_b32_e32 v8, v9, v7, vcc
	v_xor_b32_e32 v7, 0x80000000, v7
	v_xor_b32_e32 v5, v5, v8
	v_cndmask_b32_e32 v7, v7, v9, vcc
	v_cmp_class_f32_e64 vcc, v4, s89
	v_xor_b32_e32 v4, v5, v10
	v_xor_b32_e32 v7, v7, v10
	v_cndmask_b32_e32 v5, v230, v4, vcc
	v_cndmask_b32_e32 v4, v230, v7, vcc
	v_pk_mul_f32 v[44:45], v[6:7], v[4:5] op_sel_hi:[0,1]
	v_pk_mul_f32 v[4:5], v[34:35], v[34:35]
	v_readlane_b32 s68, v245, 14
	v_add_f32_e32 v4, v4, v5
	v_div_scale_f32 v5, s[0:1], v4, v4, 1.0
	v_rcp_f32_e32 v6, v5
	v_readlane_b32 s69, v245, 15
	v_add_f32_e32 v36, -1.0, v44
	v_pk_mov_b32 v[40:41], v[44:45], v[44:45] op_sel:[1,0]
	v_fma_f32 v7, -v5, v6, 1.0
	v_fmac_f32_e32 v6, v7, v6
	v_div_scale_f32 v7, vcc, 1.0, v4, 1.0
	v_mul_f32_e32 v8, v7, v6
	v_fma_f32 v9, -v5, v8, v7
	v_fmac_f32_e32 v8, v9, v6
	v_fma_f32 v5, -v5, v8, v7
	v_div_fmas_f32 v5, v5, v6, v8
	v_lshl_add_u64 v[6:7], s[66:67], 0, v[2:3]
	v_lshl_add_u64 v[30:31], s[68:69], 0, v[2:3]
	v_div_fixup_f32 v38, v5, v4, 1.0
	global_load_dwordx4 v[2:5], v[6:7], off offset:48
	global_load_dwordx4 v[10:13], v[6:7], off offset:32
	global_load_dwordx4 v[18:21], v[6:7], off offset:16
	global_load_dwordx4 v[26:29], v[6:7], off
	s_nop 0
	global_load_dwordx4 v[6:9], v[30:31], off offset:48
	global_load_dwordx4 v[14:17], v[30:31], off offset:32
	global_load_dwordx4 v[22:25], v[30:31], off offset:16
	s_nop 0
	global_load_dwordx4 v[30:33], v[30:31], off
	v_mov_b32_e32 v42, v35
	v_mov_b32_e32 v37, v45
	v_mov_b32_e32 v41, v36
	v_pk_mul_f32 v[36:37], v[42:43], v[36:37] op_sel_hi:[0,1]
	v_pk_fma_f32 v[42:43], v[34:35], v[44:45], v[36:37] op_sel:[0,1,0] op_sel_hi:[1,0,1] neg_lo:[0,0,1] neg_hi:[0,0,1]
	v_pk_fma_f32 v[34:35], v[34:35], v[40:41], v[36:37] op_sel_hi:[0,1,1]
	v_mov_b32_e32 v43, v35
	v_pk_mul_f32 v[34:35], v[38:39], v[42:43] op_sel_hi:[0,1]
	v_readlane_b32 s0, v245, 54
	v_readlane_b32 s1, v245, 55
	v_add_u32_e32 v1, v1, v147
	v_mov_b32_e32 v48, 0
	s_mov_b32 s10, 0
	v_pk_mov_b32 v[46:47], v[44:45], v[44:45] op_sel:[1,0]
	v_readlane_b32 s57, v245, 3
	v_readlane_b32 s58, v245, 4
	v_readlane_b32 s59, v245, 5
	v_readlane_b32 s60, v245, 6
	v_readlane_b32 s61, v245, 7
	v_readlane_b32 s62, v245, 8
	v_readlane_b32 s63, v245, 9
	v_readlane_b32 s64, v245, 10
	v_readlane_b32 s65, v245, 11
	v_readlane_b32 s70, v245, 16
	v_readlane_b32 s71, v245, 17
	s_waitcnt vmcnt(4)
	v_mov_b32_e32 v37, v26
	s_waitcnt vmcnt(0)
	v_mov_b32_e32 v36, v30
	v_pk_mul_f32 v[36:37], v[36:37], v[34:35]
	s_nop 0
	v_sub_f32_e32 v38, v37, v36
	v_mov_b32_e32 v36, v26
	v_mov_b32_e32 v37, v30
	v_pk_mul_f32 v[36:37], v[36:37], v[34:35]
	v_mov_b32_e32 v26, v31
	v_mov_b32_e32 v30, v27
	v_add_f32_e32 v39, v37, v36
	v_pk_mul_f32 v[36:37], v[26:27], v[34:35]
	v_pk_mul_f32 v[26:27], v[30:31], v[34:35]
	v_sub_f32_e32 v36, v37, v36
	v_add_f32_e32 v30, v27, v26
	v_mov_b32_e32 v26, v32
	v_mov_b32_e32 v27, v28
	v_pk_mul_f32 v[26:27], v[26:27], v[34:35]
	s_nop 0
	v_sub_f32_e32 v31, v27, v26
	v_mov_b32_e32 v26, v28
	v_mov_b32_e32 v27, v32
	v_pk_mul_f32 v[26:27], v[26:27], v[34:35]
	v_mov_b32_e32 v28, v33
	v_add_f32_e32 v37, v27, v26
	v_pk_mul_f32 v[26:27], v[28:29], v[34:35]
	v_mov_b32_e32 v32, v29
	v_sub_f32_e32 v28, v27, v26
	v_pk_mul_f32 v[26:27], v[32:33], v[34:35]
	s_nop 0
	v_add_f32_e32 v29, v27, v26
	v_mov_b32_e32 v26, v22
	v_mov_b32_e32 v27, v18
	v_pk_mul_f32 v[26:27], v[26:27], v[34:35]
	s_nop 0
	v_sub_f32_e32 v32, v27, v26
	v_mov_b32_e32 v26, v18
	v_mov_b32_e32 v27, v22
	v_pk_mul_f32 v[26:27], v[26:27], v[34:35]
	v_mov_b32_e32 v18, v23
	v_mov_b32_e32 v22, v19
	v_add_f32_e32 v33, v26, v27
	v_pk_mul_f32 v[26:27], v[18:19], v[34:35]
	v_pk_mul_f32 v[18:19], v[22:23], v[34:35]
	v_sub_f32_e32 v26, v27, v26
	v_add_f32_e32 v27, v18, v19
	v_mov_b32_e32 v18, v24
	v_mov_b32_e32 v19, v20
	v_pk_mul_f32 v[18:19], v[18:19], v[34:35]
	s_nop 0
	v_sub_f32_e32 v22, v19, v18
	v_mov_b32_e32 v18, v20
	v_mov_b32_e32 v19, v24
	v_pk_mul_f32 v[18:19], v[18:19], v[34:35]
	v_mov_b32_e32 v20, v25
	v_add_f32_e32 v40, v18, v19
	v_pk_mul_f32 v[18:19], v[20:21], v[34:35]
	v_mov_b32_e32 v24, v21
	v_sub_f32_e32 v20, v19, v18
	v_pk_mul_f32 v[18:19], v[24:25], v[34:35]
	s_nop 0
	v_add_f32_e32 v25, v18, v19
	v_mov_b32_e32 v18, v14
	v_mov_b32_e32 v19, v10
	v_pk_mul_f32 v[18:19], v[18:19], v[34:35]
	s_nop 0
	v_sub_f32_e32 v21, v19, v18
	v_mov_b32_e32 v18, v10
	v_mov_b32_e32 v19, v14
	v_pk_mul_f32 v[18:19], v[18:19], v[34:35]
	v_mov_b32_e32 v10, v15
	v_mov_b32_e32 v14, v11
	v_add_f32_e32 v41, v18, v19
	v_pk_mul_f32 v[18:19], v[10:11], v[34:35]
	v_pk_mul_f32 v[10:11], v[14:15], v[34:35]
	v_sub_f32_e32 v18, v19, v18
	v_add_f32_e32 v42, v10, v11
	v_mov_b32_e32 v10, v16
; __device__ __forceinline__ unsigned cvt_pk_bf16(float lo, float hi) { unsigned r; asm volatile("v_cvt_pk_bf16_f32 %0, %1, %2" : "=v"(r) : "v"(lo), "v"(hi)); return r; }
; __device__ __forceinline__ float bflo(unsigned w) { return __uint_as_float(w << 16); }
; __device__ __forceinline__ float bfhi(unsigned w) { return __uint_as_float(w & 0xffff0000u); }
; template <int MODE>
; __device__ __forceinline__ void s5_unit(const Params& P, unsigned char* wl, const int id) {
;     ...
;     { s5_setup(P, g, lane, ar, ai, Br, Bi);
;       u32x4 w[4], v[4];
; #pragma unroll
;       for (int i = 0; i < 4; ++i) { unsigned hw[4], lw[4];
; #pragma unroll
;           for (int e = 0; e < 4; ++e) { const int c0 = (i & 1) * 8 + 2 * e; const float x0 = (i < 2) ? Br[c0] : Bi[c0], x1 = (i < 2) ? Br[c0 + 1] : Bi[c0 + 1];
;               const unsigned h = cvt_pk_bf16(x0, x1); hw[e] = h; lw[e] = cvt_pk_bf16(x0 - bflo(h), x1 - bfhi(h)); }
;           w[i] = (u32x4){hw[0], hw[1], hw[2], hw[3]}; v[i] = (u32x4){lw[0], lw[1], lw[2], lw[3]}; }
;       u32x4* bt = (u32x4*)(Btab + lane * 32); bt[0] = w[0]; bt[1] = w[1]; bt[2] = w[2]; bt[3] = w[3];
;       u32x4* lt = (u32x4*)((bf16_t*)buf + lane * 32); lt[0] = v[0]; lt[1] = v[1]; lt[2] = v[2]; lt[3] = v[3]; }
;     asm volatile("s_waitcnt lgkmcnt(0)" ::: "memory");
;     const bf16x8 zf = (bf16x8){0, 0, 0, 0, 0, 0, 0, 0};
;     bf16x8 bfr[8];
; #pragma unroll
;     for (int nn = 0; nn < 8; ++nn) bfr[nn] = *(const bf16x8*)((q < 2 ? Btab : (const bf16_t*)buf) + (16 * nn + l16) * 16 + 8 * (q & 1));
;     asm volatile("s_waitcnt lgkmcnt(0)" ::: "memory");
;     ...
;     const bf16_t* arow = PROJ + (size_t)(row0 + l16) * NPROJ + C_U + g * 16 + 8 * (q & 1);
;     bf16x8 a_cur = *(const bf16x8*)arow;
;     for (int blk = 0; blk < nblk; ++blk) {
;         bf16x8 a_nxt = zf; if (blk + 1 < nblk) a_nxt = *(const bf16x8*)(arow + (size_t)(blk + 1) * 16 * NPROJ);
	v_mov_b32_e32 v11, v12
	v_pk_mul_f32 v[10:11], v[10:11], v[34:35]
	s_nop 0
	v_sub_f32_e32 v15, v11, v10
	v_mov_b32_e32 v10, v12
	v_mov_b32_e32 v11, v16
	v_pk_mul_f32 v[10:11], v[10:11], v[34:35]
	v_mov_b32_e32 v12, v17
	v_add_f32_e32 v43, v10, v11
	v_pk_mul_f32 v[10:11], v[12:13], v[34:35]
	v_mov_b32_e32 v16, v13
	v_sub_f32_e32 v12, v11, v10
	v_pk_mul_f32 v[10:11], v[16:17], v[34:35]
	s_nop 0
	v_add_f32_e32 v49, v10, v11
	v_mov_b32_e32 v10, v6
	v_mov_b32_e32 v11, v2
	v_pk_mul_f32 v[10:11], v[10:11], v[34:35]
	s_nop 0
	v_sub_f32_e32 v13, v11, v10
	v_mov_b32_e32 v10, v2
	v_mov_b32_e32 v11, v6
	v_pk_mul_f32 v[10:11], v[10:11], v[34:35]
	v_mov_b32_e32 v2, v7
	v_mov_b32_e32 v6, v3
	v_add_f32_e32 v50, v10, v11
	v_pk_mul_f32 v[10:11], v[2:3], v[34:35]
	v_pk_mul_f32 v[2:3], v[6:7], v[34:35]
	v_sub_f32_e32 v16, v11, v10
	v_add_f32_e32 v51, v2, v3
	v_mov_b32_e32 v2, v8
	v_mov_b32_e32 v3, v4
	v_pk_mul_f32 v[2:3], v[2:3], v[34:35]
	s_nop 0
	v_sub_f32_e32 v17, v3, v2
	v_mov_b32_e32 v2, v4
	v_mov_b32_e32 v3, v8
	v_pk_mul_f32 v[2:3], v[2:3], v[34:35]
	v_mov_b32_e32 v4, v9
	v_add_f32_e32 v55, v2, v3
	v_pk_mul_f32 v[2:3], v[4:5], v[34:35]
	v_mov_b32_e32 v8, v5
	v_sub_f32_e32 v19, v3, v2
	v_pk_mul_f32 v[2:3], v[8:9], v[34:35]
	s_nop 0
	v_add_f32_e32 v34, v2, v3
	v_cvt_pk_bf16_f32 v2, v38, v36
	s_nop 0
	v_lshlrev_b32_e32 v3, 16, v2
	v_and_b32_e32 v4, 0xffff0000, v2
	v_sub_f32_e32 v3, v38, v3
	v_sub_f32_e32 v4, v36, v4
	v_cvt_pk_bf16_f32 v6, v3, v4
	v_cvt_pk_bf16_f32 v3, v31, v28
	v_lshlrev_b32_e32 v36, 5, v52
	v_lshlrev_b32_e32 v4, 16, v3
	v_and_b32_e32 v5, 0xffff0000, v3
	v_sub_f32_e32 v4, v31, v4
	v_sub_f32_e32 v5, v28, v5
	v_cvt_pk_bf16_f32 v7, v4, v5
	v_cvt_pk_bf16_f32 v4, v32, v26
	v_lshlrev_b32_e32 v38, 1, v150
	v_lshlrev_b32_e32 v5, 16, v4
	v_and_b32_e32 v8, 0xffff0000, v4
	v_sub_f32_e32 v5, v32, v5
	v_sub_f32_e32 v8, v26, v8
	v_cvt_pk_bf16_f32 v8, v5, v8
	v_cvt_pk_bf16_f32 v5, v22, v20
	s_nop 0
	v_lshlrev_b32_e32 v9, 16, v5
	v_and_b32_e32 v10, 0xffff0000, v5
	v_sub_f32_e32 v9, v22, v9
	v_sub_f32_e32 v10, v20, v10
	v_cvt_pk_bf16_f32 v9, v9, v10
	v_cvt_pk_bf16_f32 v10, v21, v18
	s_nop 0
	v_lshlrev_b32_e32 v11, 16, v10
	v_and_b32_e32 v14, 0xffff0000, v10
	v_sub_f32_e32 v11, v21, v11
	v_sub_f32_e32 v14, v18, v14
	v_cvt_pk_bf16_f32 v14, v11, v14
	v_cvt_pk_bf16_f32 v11, v15, v12
	s_nop 0
	v_lshlrev_b32_e32 v18, 16, v11
	v_sub_f32_e32 v15, v15, v18
	v_and_b32_e32 v18, 0xffff0000, v11
	v_sub_f32_e32 v12, v12, v18
	v_cvt_pk_bf16_f32 v15, v15, v12
	v_cvt_pk_bf16_f32 v12, v13, v16
	s_nop 0
	v_lshlrev_b32_e32 v18, 16, v12
	v_sub_f32_e32 v13, v13, v18
	v_and_b32_e32 v18, 0xffff0000, v12
	v_sub_f32_e32 v16, v16, v18
	v_cvt_pk_bf16_f32 v16, v13, v16
	v_cvt_pk_bf16_f32 v13, v17, v19
	s_nop 0
	v_lshlrev_b32_e32 v18, 16, v13
	v_sub_f32_e32 v17, v17, v18
	v_and_b32_e32 v18, 0xffff0000, v13
	v_sub_f32_e32 v18, v19, v18
	v_cvt_pk_bf16_f32 v17, v17, v18
	v_cvt_pk_bf16_f32 v18, v39, v30
	s_nop 0
	v_lshlrev_b32_e32 v19, 16, v18
	v_and_b32_e32 v20, 0xffff0000, v18
	v_sub_f32_e32 v19, v39, v19
	v_sub_f32_e32 v20, v30, v20
	v_cvt_pk_bf16_f32 v22, v19, v20
	v_cvt_pk_bf16_f32 v19, v37, v29
	v_mov_b32_e32 v39, v0
	v_lshlrev_b32_e32 v20, 16, v19
	v_and_b32_e32 v21, 0xffff0000, v19
	v_sub_f32_e32 v20, v37, v20
	v_sub_f32_e32 v21, v29, v21
	v_cvt_pk_bf16_f32 v23, v20, v21
	v_cvt_pk_bf16_f32 v20, v33, v27
	v_mov_b32_e32 v37, v0
	v_lshlrev_b32_e32 v21, 16, v20
	v_and_b32_e32 v24, 0xffff0000, v20
	v_sub_f32_e32 v21, v33, v21
	v_sub_f32_e32 v24, v27, v24
	v_cvt_pk_bf16_f32 v24, v21, v24
	v_cvt_pk_bf16_f32 v21, v40, v25
	s_nop 0
	v_lshlrev_b32_e32 v26, 16, v21
	v_and_b32_e32 v27, 0xffff0000, v21
	v_sub_f32_e32 v26, v40, v26
	v_sub_f32_e32 v25, v25, v27
	v_cvt_pk_bf16_f32 v25, v26, v25
	v_cvt_pk_bf16_f32 v26, v41, v42
	s_nop 0
	v_lshlrev_b32_e32 v27, 16, v26
	v_and_b32_e32 v28, 0xffff0000, v26
	v_sub_f32_e32 v27, v41, v27
	v_sub_f32_e32 v28, v42, v28
	v_cvt_pk_bf16_f32 v30, v27, v28
	v_cvt_pk_bf16_f32 v27, v43, v49
	s_nop 0
	v_lshlrev_b32_e32 v28, 16, v27
	v_and_b32_e32 v29, 0xffff0000, v27
	v_sub_f32_e32 v28, v43, v28
	v_sub_f32_e32 v29, v49, v29
	v_cvt_pk_bf16_f32 v31, v28, v29
	v_cvt_pk_bf16_f32 v28, v50, v51
	v_mov_b32_e32 v49, v48
	v_lshlrev_b32_e32 v29, 16, v28
	v_and_b32_e32 v32, 0xffff0000, v28
	v_sub_f32_e32 v29, v50, v29
	v_sub_f32_e32 v32, v51, v32
	v_cvt_pk_bf16_f32 v32, v29, v32
	v_cvt_pk_bf16_f32 v29, v55, v34
	s_nop 0
	v_lshlrev_b32_e32 v33, 16, v29
	v_sub_f32_e32 v33, v55, v33
	v_and_b32_e32 v35, 0xffff0000, v29
	v_sub_f32_e32 v34, v34, v35
	v_cvt_pk_bf16_f32 v33, v33, v34
	ds_write_b128 v155, v[2:5]
	ds_write_b128 v155, v[10:13] offset:16
	ds_write_b128 v155, v[18:21] offset:32
	ds_write_b128 v155, v[26:29] offset:48
	ds_write_b128 v155, v[6:9] offset:4096
	ds_write_b128 v155, v[14:17] offset:4112
	ds_write_b128 v155, v[22:25] offset:4128
	ds_write_b128 v155, v[30:33] offset:4144
	v_mov_b64_e32 v[2:3], s[0:1]
	v_mad_i64_i32 v[2:3], s[0:1], v1, s90, v[2:3]
	s_waitcnt lgkmcnt(0)
	v_lshl_add_u64 v[2:3], v[2:3], 0, v[36:37]
	ds_read_b128 v[4:7], v183
	ds_read_b128 v[8:11], v183 offset:512
	ds_read_b128 v[12:15], v183 offset:1024
	ds_read_b128 v[16:19], v183 offset:1536
	ds_read_b128 v[20:23], v183 offset:2048
	ds_read_b128 v[24:27], v183 offset:2560
	ds_read_b128 v[28:31], v183 offset:3072
	ds_read_b128 v[32:35], v183 offset:3584
	s_waitcnt lgkmcnt(0)
	v_lshl_add_u64 v[2:3], v[2:3], 0, v[38:39]
	global_load_dwordx4 v[40:43], v[2:3], off
	v_mad_i64_i32 v[2:3], s[0:1], v1, s90, v[36:37]
	v_lshl_add_u64 v[50:51], v[170:171], 0, v[2:3]
	s_mov_b64 s[0:1], 0
	v_readfirstlane_b32 s8, v53
	v_mov_b64_e32 v[112:113], v[50:51]
	s_cmp_lt_u32 s8, 2
	s_cbranch_scc1 .Lpf0_none
	global_load_dwordx4 v[84:87], v[112:113], off
	v_add_co_u32_e32 v112, vcc, 0x48000, v112
	s_nop 1
	v_addc_co_u32_e32 v113, vcc, 0, v113, vcc
	global_load_dwordx4 v[88:91], v[112:113], off
	v_add_co_u32_e32 v112, vcc, 0x48000, v112
	s_nop 1
	v_addc_co_u32_e32 v113, vcc, 0, v113, vcc
	global_load_dwordx4 v[92:95], v[112:113], off
	v_add_co_u32_e32 v112, vcc, 0x48000, v112
	s_nop 1
	v_addc_co_u32_e32 v113, vcc, 0, v113, vcc
	global_load_dwordx4 v[96:99], v[112:113], off
	v_add_co_u32_e32 v112, vcc, 0x48000, v112
	s_nop 1
	v_addc_co_u32_e32 v113, vcc, 0, v113, vcc
	global_load_dwordx4 v[100:103], v[112:113], off
	v_add_co_u32_e32 v112, vcc, 0x48000, v112
	s_nop 1
	v_addc_co_u32_e32 v113, vcc, 0, v113, vcc
	global_load_dwordx4 v[104:107], v[112:113], off
	v_add_co_u32_e32 v112, vcc, 0x48000, v112
	s_nop 1
	v_addc_co_u32_e32 v113, vcc, 0, v113, vcc
	global_load_dwordx4 v[108:111], v[112:113], off
	s_waitcnt vmcnt(7)
	s_branch .LBB0_367
; __device__ __forceinline__ unsigned cvt_pk_bf16(float lo, float hi) { unsigned r; asm volatile("v_cvt_pk_bf16_f32 %0, %1, %2" : "=v"(r) : "v"(lo), "v"(hi)); return r; }
; __device__ __forceinline__ f32x4 mfma16(bf16x8 a, bf16x8 b, f32x4 c) { return __builtin_amdgcn_mfma_f32_16x16x32_bf16(a, b, c, 0, 0, 0); }
; template <int MODE>
; __device__ __forceinline__ void s5_unit(const Params& P, unsigned char* wl, const int id) {
;     ...
;     for (int blk = 0; blk < nblk; ++blk) {
;         bf16x8 a_nxt = zf; if (blk + 1 < nblk) a_nxt = *(const bf16x8*)(arow + (size_t)(blk + 1) * 16 * NPROJ);
;         { float* bp = buf + (4 * q) * 130 + l16; f32x4 d[8];
; #pragma unroll
;           for (int nn = 0; nn < 8; ++nn) d[nn] = mfma16(a_cur, bfr[nn], (f32x4){0.f, 0.f, 0.f, 0.f});
;           __builtin_amdgcn_sched_barrier(0); asm volatile("s_nop 15\n\ts_nop 15" ::: "memory"); __builtin_amdgcn_sched_barrier(0);
; #pragma unroll
;           for (int nn = 0; nn < 8; ++nn) { bp[16 * nn] = d[nn][0]; bp[130 + 16 * nn] = d[nn][1]; bp[260 + 16 * nn] = d[nn][2]; bp[390 + 16 * nn] = d[nn][3]; } }
;     ...
;             f32x2 bb[16];
; #pragma unroll
;             for (int t = 0; t < 16; ++t) bb[t] = *(const f32x2*)(buf + t * 130 + 2 * lane);
; #pragma unroll
;             for (int t = 0; t < 16; ++t) { const float nr_ = ar * hr - ai * hi + bb[t].x, ni_ = ar * hi + ai * hr + bb[t].y; hr = nr_; hi = ni_;
;                 if (MODE == 1) Hw[t * 68 + lane] = cvt_pk_bf16(hr, hi); }
.Lpf0_none:
	s_waitcnt vmcnt(0)
	s_branch .LBB0_367
.LBB0_366:
	s_or_b64 exec, exec, s[8:9]
	s_waitcnt lgkmcnt(7)
	v_mfma_f32_16x16x32_bf16 v[56:59], v[40:43], v[4:7], 0
	s_waitcnt lgkmcnt(6)
	v_mfma_f32_16x16x32_bf16 v[60:63], v[40:43], v[8:11], 0
	s_waitcnt lgkmcnt(5)
	v_mfma_f32_16x16x32_bf16 v[64:67], v[40:43], v[12:15], 0
	s_waitcnt lgkmcnt(4)
	v_mfma_f32_16x16x32_bf16 v[68:71], v[40:43], v[16:19], 0
	s_waitcnt lgkmcnt(3)
	v_mfma_f32_16x16x32_bf16 v[72:75], v[40:43], v[20:23], 0
	s_waitcnt lgkmcnt(2)
	v_mfma_f32_16x16x32_bf16 v[76:79], v[40:43], v[24:27], 0
	s_waitcnt lgkmcnt(1)
	v_mfma_f32_16x16x32_bf16 v[80:83], v[40:43], v[28:31], 0
	s_waitcnt lgkmcnt(0)
	v_mfma_f32_16x16x32_bf16 v[40:43], v[40:43], v[32:35], 0
	s_nop 15
	s_nop 15
	v_add_u32_e32 v1, 0x1000, v212
	v_add_u32_e32 v2, 0x1400, v212
	ds_write2_b32 v1, v56, v60 offset1:16
	ds_write2_b32 v1, v57, v61 offset0:130 offset1:146
	ds_write2_b32 v2, v58, v62 offset0:4 offset1:20
	ds_write2_b32 v2, v59, v63 offset0:134 offset1:150
	ds_write2_b32 v1, v64, v68 offset0:32 offset1:48
	ds_write2_b32 v1, v65, v69 offset0:162 offset1:178
	ds_write2_b32 v2, v66, v70 offset0:36 offset1:52
	ds_write2_b32 v2, v67, v71 offset0:166 offset1:182
	ds_write2_b32 v1, v72, v76 offset0:64 offset1:80
	ds_write2_b32 v1, v73, v77 offset0:194 offset1:210
	ds_write2_b32 v2, v74, v78 offset0:68 offset1:84
	ds_write2_b32 v2, v75, v79 offset0:198 offset1:214
	ds_write2_b32 v1, v80, v40 offset0:96 offset1:112
	ds_write2_b32 v1, v81, v41 offset0:226 offset1:242
	ds_write2_b32 v2, v82, v42 offset0:100 offset1:116
	ds_write2_b32 v2, v83, v43 offset0:230 offset1:246
	s_waitcnt lgkmcnt(0)
	v_add_u32_e32 v1, 0x1000, v218
	ds_read2_b64 v[40:43], v1 offset1:65
	ds_read2_b64 v[56:59], v1 offset0:130 offset1:195
	v_add_u32_e32 v1, 0x1800, v218
	ds_read2_b64 v[60:63], v1 offset0:4 offset1:69
	ds_read2_b64 v[64:67], v1 offset0:134 offset1:199
	v_add_u32_e32 v1, 0x2000, v218
	ds_read2_b64 v[68:71], v1 offset0:8 offset1:73
	ds_read2_b64 v[72:75], v1 offset0:138 offset1:203
	v_add_u32_e32 v1, 0x2800, v218
	ds_read2_b64 v[76:79], v1 offset0:12 offset1:77
	ds_read2_b64 v[80:83], v1 offset0:142 offset1:207
	s_mov_b64 s[8:9], 0x48000
	v_cmp_eq_u32_e32 vcc, s10, v53
	v_lshl_add_u64 v[50:51], v[50:51], 0, s[8:9]
	s_or_b64 s[0:1], vcc, s[0:1]
	s_waitcnt lgkmcnt(7)
	v_fma_f32 v236, v44, v48, v40
	v_fma_f32 v237, v44, v49, v41
	v_fma_f32 v2, -v45, v49, v236
	v_fma_f32 v3, v45, v48, v237
	v_fma_f32 v236, v44, v2, v42
	v_fma_f32 v237, v44, v3, v43
	v_fma_f32 v48, -v45, v3, v236
	v_fma_f32 v49, v45, v2, v237
	s_waitcnt lgkmcnt(6)
	v_fma_f32 v236, v44, v48, v56
	v_fma_f32 v237, v44, v49, v57
	v_fma_f32 v2, -v45, v49, v236
	v_fma_f32 v3, v45, v48, v237
	v_fma_f32 v236, v44, v2, v58
	v_fma_f32 v237, v44, v3, v59
	v_fma_f32 v48, -v45, v3, v236
	v_fma_f32 v49, v45, v2, v237
	s_waitcnt lgkmcnt(5)
	v_fma_f32 v236, v44, v48, v60
	v_fma_f32 v237, v44, v49, v61
	v_fma_f32 v2, -v45, v49, v236
	v_fma_f32 v3, v45, v48, v237
	v_fma_f32 v236, v44, v2, v62
	v_fma_f32 v237, v44, v3, v63
	v_fma_f32 v48, -v45, v3, v236
	v_fma_f32 v49, v45, v2, v237
	s_waitcnt lgkmcnt(4)
	v_fma_f32 v236, v44, v48, v64
	v_fma_f32 v237, v44, v49, v65
	v_fma_f32 v2, -v45, v49, v236
	v_fma_f32 v3, v45, v48, v237
	v_fma_f32 v236, v44, v2, v66
	v_fma_f32 v237, v44, v3, v67
	v_fma_f32 v48, -v45, v3, v236
	v_fma_f32 v49, v45, v2, v237
	s_waitcnt lgkmcnt(3)
	v_fma_f32 v236, v44, v48, v68
	v_fma_f32 v237, v44, v49, v69
	v_fma_f32 v2, -v45, v49, v236
	v_fma_f32 v3, v45, v48, v237
	v_fma_f32 v236, v44, v2, v70
	v_fma_f32 v237, v44, v3, v71
	v_fma_f32 v48, -v45, v3, v236
	v_fma_f32 v49, v45, v2, v237
	s_waitcnt lgkmcnt(2)
	v_fma_f32 v236, v44, v48, v72
	v_fma_f32 v237, v44, v49, v73
	v_fma_f32 v2, -v45, v49, v236
	v_fma_f32 v3, v45, v48, v237
	v_fma_f32 v236, v44, v2, v74
	v_fma_f32 v237, v44, v3, v75
	v_fma_f32 v48, -v45, v3, v236
	v_fma_f32 v49, v45, v2, v237
	s_waitcnt lgkmcnt(1)
	v_fma_f32 v236, v44, v48, v76
	v_fma_f32 v237, v44, v49, v77
	v_fma_f32 v2, -v45, v49, v236
	v_fma_f32 v3, v45, v48, v237
	v_fma_f32 v236, v44, v2, v78
	v_fma_f32 v237, v44, v3, v79
	v_fma_f32 v48, -v45, v3, v236
	v_fma_f32 v49, v45, v2, v237
	s_waitcnt lgkmcnt(0)
	v_fma_f32 v236, v44, v48, v80
	v_fma_f32 v237, v44, v49, v81
	v_fma_f32 v2, -v45, v49, v236
	v_fma_f32 v3, v45, v48, v237
	v_fma_f32 v236, v44, v2, v82
	v_fma_f32 v237, v44, v3, v83
	v_fma_f32 v48, -v45, v3, v236
	v_fma_f32 v49, v45, v2, v237
	v_mov_b64_e32 v[42:43], v[38:39]
	v_mov_b64_e32 v[40:41], v[36:37]
	s_andn2_b64 exec, exec, s[0:1]
	s_cbranch_execz .LBB0_375
.LBB0_367:
	v_mov_b32_e32 v2, v0
	v_mov_b32_e32 v3, v0
	s_add_i32 s10, s10, 1
	v_mov_b32_e32 v1, v0
	v_mov_b64_e32 v[38:39], v[2:3]
	v_cmp_lt_u32_e32 vcc, s10, v53
	v_mov_b64_e32 v[36:37], v[0:1]
	s_and_saveexec_b64 s[8:9], vcc
	s_cbranch_execz .LBB0_366
	s_cmp_eq_u32 s10, 1
	s_cbranch_scc1 .Lpf0_c1
	s_cmp_eq_u32 s10, 2
	s_cbranch_scc1 .Lpf0_c2
	s_cmp_eq_u32 s10, 3
	s_cbranch_scc1 .Lpf0_c3
	s_cmp_eq_u32 s10, 4
	s_cbranch_scc1 .Lpf0_c4
	s_cmp_eq_u32 s10, 5
	s_cbranch_scc1 .Lpf0_c5
	s_cmp_eq_u32 s10, 6
	s_cbranch_scc1 .Lpf0_c6
	s_cmp_eq_u32 s10, 7
	s_cbranch_scc1 .Lpf0_c7
	s_branch .LBB0_366
.Lpf0_c1:
	s_waitcnt vmcnt(6)
	v_mov_b64_e32 v[36:37], v[84:85]
	v_mov_b64_e32 v[38:39], v[86:87]
	s_branch .LBB0_366
.Lpf0_c2:
	s_waitcnt vmcnt(5)
	v_mov_b64_e32 v[36:37], v[88:89]
	v_mov_b64_e32 v[38:39], v[90:91]
	s_branch .LBB0_366
.Lpf0_c3:
	s_waitcnt vmcnt(4)
	v_mov_b64_e32 v[36:37], v[92:93]
	v_mov_b64_e32 v[38:39], v[94:95]
	s_branch .LBB0_366
.Lpf0_c4:
	s_waitcnt vmcnt(3)
	v_mov_b64_e32 v[36:37], v[96:97]
	v_mov_b64_e32 v[38:39], v[98:99]
	s_branch .LBB0_366
.Lpf0_c5:
	s_waitcnt vmcnt(2)
	v_mov_b64_e32 v[36:37], v[100:101]
	v_mov_b64_e32 v[38:39], v[102:103]
	s_branch .LBB0_366
.Lpf0_c6:
	s_waitcnt vmcnt(1)
	v_mov_b64_e32 v[36:37], v[104:105]
	v_mov_b64_e32 v[38:39], v[106:107]
	s_branch .LBB0_366
.Lpf0_c7:
	s_waitcnt vmcnt(0)
	v_mov_b64_e32 v[36:37], v[108:109]
	v_mov_b64_e32 v[38:39], v[110:111]
	s_branch .LBB0_366
